# FoX pair loop: waves 4-7 start each pair s_sleep 5 later (de-lockstep SIMD partners)
# baseline (speedup 1.0000x reference)
; #define LAS3 __attribute__((address_space(3)))
; __device__ __forceinline__ void fox_unit(int b, int hh, int qb, const bf16_t* Q, const bf16_t* __restrict__ K, const bf16_t* __restrict__ V, bf16_t* O, ...
;     ...
;     const short one = (short)0x3F80;
;     const bf16x8 onesA = (bf16x8){one, one, one, one, one, one, one, one};
;     const bf16x8 qones = hi ? (bf16x8){0, 0, 0, 0, 0, 0, 0, 0} : (bf16x8){one, one, one, 0, 0, 0, 0, 0};
;     f32x16 o0, o1, lacc, cinit;
; #pragma unroll
;     for (int r = 0; r < 16; ++r) { o0[r] = 0.f; o1[r] = 0.f; lacc[r] = 0.f; cinit[r] = ft2 - fminf(zq, 60.0f); }
;     const float mref = fminf(zq, 60.0f);
;     volatile LAS3 unsigned* flags = (volatile LAS3 unsigned*)(shm + L_FLAG);
;     const LAS3 unsigned char* kp0 = shm + L_K + hi * 1024 + r32 * 16;
;     const LAS3 unsigned char* vp0 = shm + L_V + ((lane >> 4) & 1) * 32 + (lane & 3) * 8 + (4 * hi + ((lane & 15) >> 2)) * 64;
;     const LAS3 unsigned char* fp0 = shm + L_F + r32 * 16;
.LBB0_355:
	v_writelane_b32 v249, s74, 25
	s_nop 1
	v_writelane_b32 v249, s75, 26
	v_writelane_b32 v249, s90, 27
	v_writelane_b32 v249, s59, 28
	v_writelane_b32 v249, s88, 29
	s_nop 1
	v_writelane_b32 v249, s89, 30
	v_writelane_b32 v249, s68, 31
	s_nop 1
	v_writelane_b32 v249, s69, 32
	v_writelane_b32 v249, s70, 33
	v_writelane_b32 v249, s71, 34
	v_writelane_b32 v249, s64, 35
	s_nop 1
	v_writelane_b32 v249, s65, 36
	v_writelane_b32 v249, s62, 37
	s_nop 1
	v_writelane_b32 v249, s63, 38
	v_writelane_b32 v249, s60, 39
	s_nop 1
	v_writelane_b32 v249, s61, 40
	s_or_b64 exec, exec, s[0:1]
	s_add_u32 s0, s66, 0x1c00000
	s_addc_u32 s1, s67, 0
	s_add_u32 s88, s66, 0xb000000
	s_addc_u32 s95, s67, 0
	v_writelane_b32 v249, s0, 41
	s_add_u32 s96, s66, 0xf000000
	s_addc_u32 s97, s67, 0
	v_writelane_b32 v249, s1, 42
	s_add_u32 s93, s66, 0x13000000
	v_writelane_b32 v249, s66, 43
	v_cmp_eq_u32_e64 s[0:1], 0, v180
	s_addc_u32 s94, s67, 0
	v_writelane_b32 v249, s67, 44
	v_writelane_b32 v249, s0, 45
	v_lshlrev_b32_e32 v7, 1, v178
	v_and_b32_e32 v8, 0xc0, v130
	v_writelane_b32 v249, s1, 46
	v_cmp_ne_u32_e64 s[0:1], 0, v180
	v_and_b32_e32 v4, 24, v181
	v_and_b32_e32 v7, 32, v7
	v_writelane_b32 v249, s0, 47
	v_lshl_or_b32 v8, v185, 8, v8
	v_or3_b32 v8, v8, v7, v4
	v_writelane_b32 v249, s1, 48
	s_add_i32 s1, 0, 0x10c00
	v_writelane_b32 v249, s1, 49
	s_add_i32 s1, 0, 0x10800
	v_writelane_b32 v249, s1, 50
	s_add_i32 s1, 0, 0x1f004
	v_writelane_b32 v249, s1, 51
	s_add_i32 s1, 0, 0x1f008
	s_add_i32 s0, 0, 0x1f040
	v_writelane_b32 v249, s1, 52
	v_add_u32_e32 v139, 0, v8
	v_lshlrev_b32_e32 v8, 2, v185
	v_lshrrev_b32_e32 v9, 2, v178
	v_writelane_b32 v249, s0, 53
	v_and_or_b32 v9, v9, 3, v8
	v_writelane_b32 v249, s93, 54
	v_add_u32_e32 v7, 0, v7
	v_lshlrev_b32_e32 v9, 6, v9
	v_writelane_b32 v249, s94, 55
	v_lshlrev_b32_e32 v5, 10, v185
	v_lshlrev_b32_e32 v6, 4, v182
	v_add3_u32 v165, v7, v4, v9
	v_mov_b32_e32 v7, 0x3f80
	v_cmp_gt_u32_e64 s[8:9], 32, v180
	v_writelane_b32 v249, s88, 56
	s_waitcnt lgkmcnt(0)
	v_lshlrev_b32_e32 v2, 10, v180
	v_mov_b32_e32 v3, 0
	v_add3_u32 v137, 0, v5, v6
	v_lshlrev_b32_e32 v140, 10, v183
	s_add_i32 s92, 0, 0x10000
	v_cndmask_b32_e64 v115, 0, v7, s[8:9]
	v_mov_b32_e32 v7, 0x3f803f80
	v_sub_u32_e32 v167, v8, v182
	v_or_b32_e32 v5, v5, v6
	v_writelane_b32 v249, s95, 57
	v_lshrrev_b32_e32 v135, 2, v180
	v_lshlrev_b32_e32 v134, 10, v182
	v_lshlrev_b32_e32 v136, 3, v185
	s_mov_b32 s81, 0
	v_mul_u32_u24_e32 v162, 0x90, v182
	v_lshlrev_b32_e32 v163, 4, v184
	v_lshlrev_b32_e32 v138, 3, v184
	v_mul_u32_u24_e32 v164, 0x90, v183
	v_mov_b32_e32 v141, v3
	v_or_b32_e32 v142, 0x2000, v140
	v_mov_b32_e32 v143, v3
	v_or_b32_e32 v144, 0x4000, v140
	v_mov_b32_e32 v145, v3
	v_or_b32_e32 v146, 0x6000, v140
	v_mov_b32_e32 v147, v3
	v_lshlrev_b32_e32 v148, 11, v180
	v_mov_b32_e32 v149, v3
	v_lshlrev_b32_e32 v150, 7, v180
	v_mov_b32_e32 v151, v3
	v_add_u32_e32 v166, s92, v6
	s_mov_b32 s76, 0x3f803f80
	v_cndmask_b32_e64 v114, 0, v7, s[8:9]
	v_mov_b32_e32 v116, v3
	v_mov_b32_e32 v117, v3
	v_add_u32_e32 v168, 0xffffe100, v167
	v_add_u32_e32 v169, 0, v5
	v_add_u32_e32 v170, 0xffffe0c0, v167
	v_add_u32_e32 v171, 0xffffe080, v167
	v_lshlrev_b32_e32 v152, 1, v2
	v_mov_b32_e32 v172, 0x260
	s_add_i32 s89, 0, 0x1f00c
	s_add_i32 s90, 0, 0x1f014
	s_add_i32 s91, 0, 0x1f018
	s_add_i32 s4, 0, 0x1f01c
	v_mov_b32_e32 v173, s0
	v_lshlrev_b32_e32 v154, 1, v4
	v_mov_b32_e32 v174, 0xff800000
	v_writelane_b32 v249, s96, 58
	s_barrier
	v_writelane_b32 v249, s97, 59
	v_lshrrev_b32_e32 v186, 6, v178
	s_nop 0
	v_readfirstlane_b32 s98, v186
	s_branch .LBB0_359

; #define ATT_WAIT_BAR() asm volatile("s_waitcnt vmcnt(0) lgkmcnt(0)\n\ts_barrier" ::: "memory")
; __device__ __forceinline__ void fox_unit(int b, int hh, int qb, const bf16_t* Q, const bf16_t* __restrict__ K, const bf16_t* __restrict__ V, bf16_t* O, ...
;     ...
;         ATT_WAIT_BAR();
;         if (jp == NT / 2 - 1) { unsigned a = 0;
; #pragma unroll
;             for (int w = 0; w < 8; ++w) a |= flags[w];
;             excess = __builtin_amdgcn_readfirstlane(a) != 0u; }
.LBB0_420:
	s_waitcnt vmcnt(0) lgkmcnt(0)
	s_barrier
	s_cmp_lt_u32 s98, 4
	s_cbranch_scc1 .Lfox_nostagger
	s_sleep 5
.Lfox_nostagger:
	v_sub_co_u32_e64 v2, s[12:13], s3, 1
	s_andn2_b64 vcc, exec, s[12:13]
	v_readfirstlane_b32 s97, v2
	s_cbranch_vccnz .LBB0_422
	s_add_i32 s7, 0, 0x1f000
	v_mov_b32_e32 v2, s7
	v_readlane_b32 s7, v249, 51
	ds_read_b32 v2, v2
	v_mov_b32_e32 v6, s90
	v_mov_b32_e32 v4, s7
	v_readlane_b32 s7, v249, 52
	ds_read_b32 v4, v4
	v_mov_b32_e32 v7, s91
	v_mov_b32_e32 v5, s7
	ds_read_b32 v5, v5
	s_add_i32 s7, 0, 0x1f010
	s_waitcnt lgkmcnt(1)
	v_or_b32_e32 v2, v4, v2
	v_mov_b32_e32 v4, s89
	ds_read_b32 v4, v4
	s_waitcnt lgkmcnt(1)
	v_or_b32_e32 v2, v2, v5
	v_mov_b32_e32 v5, s7
	ds_read_b32 v5, v5
	ds_read_b32 v6, v6
	ds_read_b32 v7, v7
	v_mov_b32_e32 v8, s4
	ds_read_b32 v8, v8
	s_waitcnt lgkmcnt(4)
	v_or_b32_e32 v2, v2, v4
	s_waitcnt lgkmcnt(3)
	v_or_b32_e32 v2, v2, v5
	s_waitcnt lgkmcnt(2)
	v_or_b32_e32 v2, v2, v6
	s_waitcnt lgkmcnt(1)
	v_or_b32_e32 v2, v2, v7
	s_waitcnt lgkmcnt(0)
	v_or_b32_e32 v2, v2, v8
	s_nop 0
	v_readfirstlane_b32 s7, v2
	s_cmp_lg_u32 s7, 0
	s_cselect_b64 s[84:85], -1, 0

; __global__ void __launch_bounds__(NWAVES * 64, 2) fwd_megakernel(Args args) {
	.amdhsa_kernel _Z14fwd_megakernel4Args
		.amdhsa_group_segment_fixed_size 0
		.amdhsa_private_segment_fixed_size 0
		.amdhsa_kernarg_size 384
		.amdhsa_user_sgpr_count 2
		.amdhsa_user_sgpr_dispatch_ptr 0
		.amdhsa_user_sgpr_queue_ptr 0
		.amdhsa_user_sgpr_kernarg_segment_ptr 1
		.amdhsa_user_sgpr_dispatch_id 0
		.amdhsa_user_sgpr_kernarg_preload_length 0
		.amdhsa_user_sgpr_kernarg_preload_offset 0
		.amdhsa_user_sgpr_private_segment_size 0
		.amdhsa_uses_dynamic_stack 0
		.amdhsa_enable_private_segment 0
		.amdhsa_system_sgpr_workgroup_id_x 1
		.amdhsa_system_sgpr_workgroup_id_y 0
		.amdhsa_system_sgpr_workgroup_id_z 0
		.amdhsa_system_sgpr_workgroup_info 0
		.amdhsa_system_vgpr_workitem_id 2
		.amdhsa_next_free_vgpr 250
		.amdhsa_next_free_sgpr 100
		.amdhsa_accum_offset 252
		.amdhsa_reserve_vcc 1
		.amdhsa_float_round_mode_32 0
		.amdhsa_float_round_mode_16_64 0
		.amdhsa_float_denorm_mode_32 3
		.amdhsa_float_denorm_mode_16_64 3
		.amdhsa_dx10_clamp 1
		.amdhsa_ieee_mode 1
		.amdhsa_fp16_overflow 0
		.amdhsa_tg_split 0
		.amdhsa_exception_fp_ieee_invalid_op 0
		.amdhsa_exception_fp_denorm_src 0
		.amdhsa_exception_fp_ieee_div_zero 0
		.amdhsa_exception_fp_ieee_overflow 0
		.amdhsa_exception_fp_ieee_underflow 0
		.amdhsa_exception_fp_ieee_inexact 0
		.amdhsa_exception_int_div_zero 0
	.end_amdhsa_kernel

; __global__ void __launch_bounds__(NWAVES * 64, 2) fwd_megakernel(Args args) {
amdhsa.kernels:
  - .agpr_count:     0
    .args:
      - .offset:         0
        .size:           128
        .value_kind:     by_value
      - .offset:         128
        .size:           4
        .value_kind:     hidden_block_count_x
      - .offset:         132
        .size:           4
        .value_kind:     hidden_block_count_y
      - .offset:         136
        .size:           4
        .value_kind:     hidden_block_count_z
      - .offset:         140
        .size:           2
        .value_kind:     hidden_group_size_x
      - .offset:         142
        .size:           2
        .value_kind:     hidden_group_size_y
      - .offset:         144
        .size:           2
        .value_kind:     hidden_group_size_z
      - .offset:         146
        .size:           2
        .value_kind:     hidden_remainder_x
      - .offset:         148
        .size:           2
        .value_kind:     hidden_remainder_y
      - .offset:         150
        .size:           2
        .value_kind:     hidden_remainder_z
      - .offset:         168
        .size:           8
        .value_kind:     hidden_global_offset_x
      - .offset:         176
        .size:           8
        .value_kind:     hidden_global_offset_y
      - .offset:         184
        .size:           8
        .value_kind:     hidden_global_offset_z
      - .offset:         192
        .size:           2
        .value_kind:     hidden_grid_dims
      - .offset:         216
        .size:           8
        .value_kind:     hidden_multigrid_sync_arg
      - .offset:         248
        .size:           4
        .value_kind:     hidden_dynamic_lds_size
    .group_segment_fixed_size: 0
    .kernarg_segment_align: 8
    .kernarg_segment_size: 384
    .language:       OpenCL C
    .language_version:
      - 2
      - 0
    .max_flat_workgroup_size: 512
    .name:           _Z14fwd_megakernel4Args
    .private_segment_fixed_size: 0
    .sgpr_count:     106
    .sgpr_spill_count: 65
    .symbol:         _Z14fwd_megakernel4Args.kd
    .uniform_work_group_size: 1
    .uses_dynamic_stack: false
    .vgpr_count:     250
    .vgpr_spill_count: 0
    .wavefront_size: 64
